# RWKV: W operand stored [v][t] and read as 8 b128 per wave in the substitution stage, stage-4 LDS reads hoisted, loop-invariant constant vectors kept in registers
# speedup vs baseline: 1.0253x; 1.0032x over previous
; #define LAS __attribute__((address_space(3)))
; __device__ __forceinline__ unsigned pk2(float lo, float hi) { const f32x2 v = {lo, hi}; return __builtin_bit_cast(unsigned, __builtin_convertvector(v, bf16x2_t)); }
; __device__ __forceinline__ unsigned f2bf(float f) { return pk2(f, 0.f) & 0xffffu; }
; __device__ __forceinline__ f32x4 mfma16(bf16x8 bfrag, bf16x8 afrag, f32x4 acc) { return __builtin_amdgcn_mfma_f32_16x16x32_bf16(bfrag, afrag, acc, 0, 0, 0); }
; __device__ __forceinline__ void rwkv_chain(LAS unsigned char* lds, int cid, const bf16_t* P0, const float* mu, const float* w0, const float* w2, const float* a0, const float* a2, ...
;     ...
;     const int vt = wid >> 1, tt2 = wid & 1;
;     f32x4 st[2]; st[0] = (f32x4){0.f, 0.f, 0.f, 0.f}; st[1] = st[0];
;     __syncthreads();
;     const bf16_t* Pb = P0 + (size_t)b * SEQ * ABPAD;
;     u32x2 rc[5], rpv[5], rnx[5]; unsigned short gcv = 0, gpv = 0, gnv = 0;
;     const unsigned voff = (unsigned)((((int)threadIdx.x >> 4) * ABPAD + ((int)threadIdx.x & 15) * 4) * 2);
;     ...
;     RW_ISSUE(dir ? 127 * 32 : 0);
;     ...
;         { RW_IDS const bf16x8 uf = ldsfrag(Ub, 40, vt * 16, 0, fr, fq);
;           oacc = mfma16(ldsfrag(MbrT, 40, tt2 * 16, 0, fr, fq), uf, oacc);
; #pragma unroll
;           for (int e = 0; e < 4; ++e) { const int sidx = tt2 * 16 + fq * 4 + e, tok = dir ? 31 - sidx : sidx;
;               ORW[(size_t)dir * T * 512 + ((size_t)b * SEQ + t0 + tok) * 512 + h * 64 + vt * 16 + fr] = (bf16_t)f2bf(oacc[e]); }
; #pragma unroll
;           for (int n2 = 0; n2 < 2; ++n2) { const int kt = tt2 * 2 + n2; st[n2] = mfma16(ldsfrag(BtT, 40, kt * 16, 0, fr, fq), uf, st[n2]);
;               const f32x4 gl = *(const LAS f32x4*)(gL + kt * 16 + fq * 4); st[n2] = st[n2] * gl;
;               u32x2 o; o.x = pk2(st[n2][0], st[n2][1]); o.y = pk2(st[n2][2], st[n2][3]); *(LAS u32x2*)(S0b + (vt * 16 + fr) * 72 + kt * 16 + fq * 4) = o; } }
.LBB0_486:
	s_lshl_b64 s[40:41], s[12:13], 12
	s_lshl_b64 s[2:3], s[38:39], 1
	s_add_u32 s42, s57, s2
	s_addc_u32 s43, s63, s3
	s_lshl_b32 s1, s1, 2
	v_readlane_b32 s2, v253, 30
	v_readlane_b32 s3, v253, 31
	s_add_u32 s44, s2, s1
	s_addc_u32 s45, s3, 0
	s_and_b64 s[2:3], s[10:11], exec
	s_cselect_b32 s90, 1, -1
	s_lshl_b32 s1, s87, 26
	v_readlane_b32 s2, v253, 21
	v_readlane_b32 s3, v253, 22
	s_add_u32 s1, s2, s1
	s_addc_u32 s2, s3, 0
	s_lshl_b32 s0, s0, 1
	s_add_u32 s91, s1, s0
	s_addc_u32 s92, s2, 0
	s_and_b64 s[0:1], s[10:11], exec
	s_movk_i32 s8, 0x1e00
	s_movk_i32 s9, 0x1d00
	s_movk_i32 s12, 0x1b00
	s_movk_i32 s13, 0x1a00
	s_movk_i32 s14, 0x1900
	s_movk_i32 s15, 0x1800
	s_movk_i32 s16, 0x1700
	s_movk_i32 s17, 0x1600
	s_movk_i32 s46, 0x1500
	s_movk_i32 s47, 0x1400
	s_movk_i32 s48, 0x1300
	s_movk_i32 s49, 0x1200
	s_movk_i32 s5, 0x1100
	s_cselect_b32 s93, 0x1f00, 0
	s_cselect_b32 s94, s8, 0x100
	s_cselect_b32 s95, s9, 0x200
	s_cselect_b32 s96, s62, 0x300
	s_cselect_b32 s97, s12, 0x400
	s_cselect_b32 s22, s13, 0x500
	s_cselect_b32 s23, s14, 0x600
	s_cselect_b32 s18, s15, 0x700
	s_cselect_b32 s19, s16, 0x800
	s_cselect_b32 s2, s17, 0x900
	s_cselect_b32 s3, s46, 0xa00
	s_cselect_b32 s56, s47, 0xb00
	s_cselect_b32 s57, s48, 0xc00
	s_cselect_b32 s0, s49, 0xd00
	s_cselect_b32 s1, s5, 0xe00
	s_lshl_b32 s4, s87, 8
	s_and_b64 s[6:7], s[10:11], exec
	s_cselect_b32 s5, 0xe00, s5
	s_cselect_b32 s60, 0xd00, s49
	s_cselect_b32 s61, 0xc00, s48
	s_cselect_b32 s63, 0xb00, s47
	s_cselect_b32 s64, 0xa00, s46
	s_cselect_b32 s65, 0x900, s17
	s_cselect_b32 s66, 0x800, s16
	s_cselect_b32 s67, 0x700, s15
	s_cselect_b32 s68, 0x600, s14
	s_cselect_b32 s69, 0x500, s13
	s_cselect_b32 s70, 0x400, s12
	s_cselect_b32 s71, 0x300, s62
	s_cselect_b32 s72, 0x200, s9
	s_cselect_b32 s73, 0x100, s8
	s_cselect_b32 s8, 0, 0x1f00
	s_sub_i32 s9, 0, s4
	s_mov_b64 s[46:47], 0
	s_movk_i32 s6, 0xfc0
	v_mov_b32_e32 v1, v0
	v_mov_b32_e32 v2, v0
	v_mov_b32_e32 v3, v0
	v_mov_b32_e32 v4, v0
	v_mov_b32_e32 v5, v0
	v_mov_b32_e32 v6, v0
	v_mov_b32_e32 v7, v0
	v_and_b32_e32 v9, 15, v200
	v_lshl_add_u32 v8, v9, 4, s33
	v_lshl_add_u32 v9, v9, 2, s33
	ds_read_b128 v[232:235], v8
	ds_read_b128 v[236:239], v8 offset:256
	ds_read_b128 v[240:243], v8 offset:512
	ds_read_b128 v[244:247], v8 offset:768
	ds_read_b128 v[248:251], v8 offset:1024
	ds_read_b128 v[210:213], v8 offset:1280
	ds_read_b128 v[214:217], v8 offset:1536
	ds_read_b128 v[218:221], v8 offset:1792
	ds_read_b128 v[222:225], v8 offset:2048
	ds_read_b128 v[226:229], v8 offset:2304
	ds_read_b32 v230, v9 offset:2560
	s_waitcnt vmcnt(0) lgkmcnt(0)
	s_branch .LBB0_489
.LBB0_488:
	v_mov_b32_e32 v12, v200
	s_waitcnt lgkmcnt(0)
	s_barrier
	s_nop 0
	v_readfirstlane_b32 s12, v12
	s_bfe_u32 s7, s12, 0x10006
	v_and_b32_e32 v22, 15, v12
	s_ashr_i32 s13, s12, 3
	s_lshl_b32 s14, s7, 4
	v_bfe_u32 v23, v12, 4, 2
	v_bfi_b32 v24, -16, s13, v12
	v_or_b32_e32 v16, s14, v22
	s_and_b32 s12, s13, -16
	v_mul_lo_u32 v12, v24, s83
	v_lshlrev_b32_e32 v25, 4, v23
	v_mul_u32_u24_e32 v16, 0x50, v16
	s_add_i32 s13, 0, 0x24600
	v_add3_u32 v12, 0, v12, v25
	v_add3_u32 v16, s13, v16, v25
	ds_read_b128 v[12:15], v12 offset:58368
	ds_read_b128 v[16:19], v16
	s_add_i32 s15, 0, 0x1c400
	v_lshl_or_b32 v26, s7, 5, v22
	v_add_u32_e32 v27, s15, v25
	v_or_b32_e32 v29, 16, v26
	v_mad_u32_u24 v28, v26, s83, v27
	v_mad_u32_u24 v29, v29, s83, v27
	s_lshl_b32 s15, s7, 7
	v_add_u32_e32 v30, s15, v25
	v_add_u32_e32 v30, 0x25a00, v30
	ds_read_b128 v[114:117], v28
	ds_read_b128 v[118:121], v29
	ds_read_b128 v[122:125], v30
	ds_read_b128 v[126:129], v30 offset:64
	s_ashr_i32 s13, s12, 31
	s_lshl_b64 s[12:13], s[12:13], 1
	s_add_u32 s12, s91, s12
	s_addc_u32 s13, s92, s13
	v_mul_lo_u32 v31, v24, s76
	v_lshlrev_b32_e32 v32, 3, v23
	s_lshl_b32 s15, s7, 6
	v_add_u32_e32 v31, s85, v31
	v_add3_u32 v32, v31, v32, s15
	s_movk_i32 s16, 0x400
	s_and_b64 vcc, s[10:11], exec
	s_cselect_b32 s16, 0xfffffc00, s16
	s_cselect_b32 s17, -1, 0
	s_waitcnt lgkmcnt(4)
	v_mfma_f32_16x16x32_bf16 v[8:11], v[16:19], v[12:15], v[8:11]
	s_waitcnt lgkmcnt(3)
	v_mfma_f32_16x16x32_bf16 v[0:3], v[114:117], v[12:15], v[0:3]
	s_waitcnt lgkmcnt(2)
	v_mfma_f32_16x16x32_bf16 v[4:7], v[118:121], v[12:15], v[4:7]
	v_lshlrev_b32_e32 v16, 1, v22
	v_mov_b32_e32 v17, v38
	v_lshlrev_b32_e32 v18, 2, v23
	v_lshl_add_u64 v[16:17], s[12:13], 0, v[16:17]
	s_add_i32 s12, s46, s14
	v_add_u32_e32 v26, s12, v18
	v_or_b32_e32 v18, s14, v18
	v_sub_u32_e32 v27, s6, v18
	v_add_u32_e32 v18, 63, v27
	v_cndmask_b32_e64 v18, v26, v18, s[10:11]
	v_or_b32_e32 v18, s40, v18
	v_mov_b32_e32 v19, s41
	v_lshlrev_b64 v[20:21], 10, v[18:19]
	v_lshl_add_u64 v[20:21], v[16:17], 0, v[20:21]
	v_cvt_pk_bf16_f32 v26, v8, v8
	v_cvt_pk_bf16_f32 v27, v9, v9
	v_cvt_pk_bf16_f32 v28, v10, v10
	v_cvt_pk_bf16_f32 v29, v11, v11
	global_store_short v[20:21], v26, off
	v_lshl_add_u64 v[20:21], v[20:21], 0, s[16:17]
	global_store_short v[20:21], v27, off
	v_lshl_add_u64 v[20:21], v[20:21], 0, s[16:17]
	global_store_short v[20:21], v28, off
	v_lshl_add_u64 v[20:21], v[20:21], 0, s[16:17]
	global_store_short v[20:21], v29, off
	s_waitcnt lgkmcnt(0)
	v_pk_mul_f32 v[2:3], v[2:3], v[124:125]
	v_pk_mul_f32 v[0:1], v[0:1], v[122:123]
	v_pk_mul_f32 v[6:7], v[6:7], v[128:129]
	v_pk_mul_f32 v[4:5], v[4:5], v[126:127]
	v_cvt_pk_bf16_f32 v9, v2, v3
	v_cvt_pk_bf16_f32 v8, v0, v1
	v_cvt_pk_bf16_f32 v11, v6, v7
	v_cvt_pk_bf16_f32 v10, v4, v5
	ds_write_b64 v32, v[8:9]
	ds_write_b64 v32, v[10:11] offset:32
	s_add_u32 s46, s46, 32
	s_addc_u32 s47, s47, 0
	s_sub_i32 s6, s6, 32
	s_cmpk_lg_i32 s46, 0x1000
	s_cbranch_scc0 .LBB0_449
; #define LAS __attribute__((address_space(3)))
; __device__ __forceinline__ unsigned pk2(float lo, float hi) { const f32x2 v = {lo, hi}; return __builtin_bit_cast(unsigned, __builtin_convertvector(v, bf16x2_t)); }
; __device__ __forceinline__ unsigned f2bf(float f) { return pk2(f, 0.f) & 0xffffu; }
; __device__ __forceinline__ float frcp(float x) { return __builtin_amdgcn_rcpf(x); }
; __device__ __forceinline__ float sigmoidf_(float x) { return frcp(1.0f + __expf(-x)); }
; __device__ __forceinline__ void rwkv_chain(LAS unsigned char* lds, int cid, const bf16_t* P0, const float* mu, const float* w0, const float* w2, const float* a0, const float* a2, ...
;     ...
;         { const int tok = tid >> 4, c4 = (tid & 15) * 4;
; #pragma unroll
;         for (int i = 0; i < 5; ++i) {
;             const f32x4 mu4 = *(const LAS f32x4*)(cst + (5 + i) * 64 + c4);
;             const f32x4 cv = (f32x4){bflo(rc[i].x), bfhi(rc[i].x), bflo(rc[i].y), bfhi(rc[i].y)};
;             const f32x4 pv = (f32x4){bflo(rpv[i].x), bfhi(rpv[i].x), bflo(rpv[i].y), bfhi(rpv[i].y)}, nv = (f32x4){bflo(rnx[i].x), bfhi(rnx[i].x), bflo(rnx[i].y), bfhi(rnx[i].y)};
;             const f32x4 xv = cv + mu4 * ((pv + nv) * 0.5f - cv);
;             if (i == 0) *(LAS f32x4*)(rS + tok * 64 + c4) = xv;
;             else if (i == 1) *(LAS f32x4*)(kS + tok * 64 + c4) = xv;
;             else if (i == 2) *(LAS f32x4*)(vS + tok * 64 + c4) = xv;
;             else if (i == 3) { float th[4];
; #pragma unroll
;                 for (int e = 0; e < 4; ++e) { const float ex = __expf(2.f * xv[e]); th[e] = 1.f - 2.f * frcp(ex + 1.f); }
;                 u32x2 w; w.x = pk2(th[0], th[1]); w.y = pk2(th[2], th[3]); *(LAS u32x2*)(wdB + tok * 72 + c4) = w; }
;             else { u32x2 w; w.x = pk2(xv[0], xv[1]); w.y = pk2(xv[2], xv[3]); *(LAS u32x2*)(adB + tok * 72 + c4) = w; }
;         } }
;         if (dir == 0) {
;             const int tok = tid >> 4, c = tid & 15, t = t0 + tok;
;             const float cur = bf2f(gcv), prv = bf2f(gpv), nxt = bf2f(gnv);
;             const float x = cur + cst[10 * 64 + c] * (0.5f * (prv + nxt) - cur);
;             SG[((size_t)b * SEQ + t) * 128 + h * 16 + c] = (bf16_t)f2bf(sigmoidf_(x));
.LBB0_489:
	v_mov_b32_e32 v8, v200
	s_waitcnt vmcnt(4)
	v_lshlrev_b32_e32 v16, 16, v57
	v_ashrrev_i32_e32 v9, 4, v8
	v_and_b32_e32 v8, 15, v8
	v_lshl_add_u32 v25, v8, 4, 0
	v_and_b32_e32 v17, 0xffff0000, v57
	v_lshlrev_b32_e32 v20, 16, v55
	v_and_b32_e32 v21, 0xffff0000, v55
	v_lshlrev_b32_e32 v14, 16, v56
	v_and_b32_e32 v15, 0xffff0000, v56
	v_lshlrev_b32_e32 v18, 16, v54
	v_and_b32_e32 v19, 0xffff0000, v54
	v_pk_add_f32 v[16:17], v[20:21], v[16:17]
	v_lshlrev_b32_e32 v20, 16, v53
	v_and_b32_e32 v21, 0xffff0000, v53
	v_pk_add_f32 v[14:15], v[18:19], v[14:15]
	v_lshlrev_b32_e32 v18, 16, v52
	v_and_b32_e32 v19, 0xffff0000, v52
	v_xor_b32_e32 v23, 0x80000000, v21
	v_xor_b32_e32 v22, 0x80000000, v20
	v_pk_fma_f32 v[16:17], v[16:17], 0.5, v[22:23] op_sel_hi:[1,0,1]
	v_xor_b32_e32 v23, 0x80000000, v19
	v_xor_b32_e32 v22, 0x80000000, v18
	v_pk_fma_f32 v[14:15], v[14:15], 0.5, v[22:23] op_sel_hi:[1,0,1]
	v_lshl_add_u32 v27, v9, 8, v25
	v_pk_fma_f32 v[10:11], v[14:15], v[210:211], v[18:19]
	v_pk_fma_f32 v[12:13], v[16:17], v[212:213], v[20:21]
	ds_write_b128 v27, v[10:13]
	v_lshlrev_b32_e32 v16, 16, v61
	v_and_b32_e32 v17, 0xffff0000, v61
	v_lshlrev_b32_e32 v20, 16, v63
	v_and_b32_e32 v21, 0xffff0000, v63
	v_lshlrev_b32_e32 v14, 16, v60
	v_and_b32_e32 v15, 0xffff0000, v60
	v_lshlrev_b32_e32 v18, 16, v62
	v_and_b32_e32 v19, 0xffff0000, v62
	v_pk_add_f32 v[16:17], v[20:21], v[16:17]
	v_lshlrev_b32_e32 v20, 16, v59
	v_and_b32_e32 v21, 0xffff0000, v59
	v_pk_add_f32 v[14:15], v[18:19], v[14:15]
	v_lshlrev_b32_e32 v18, 16, v58
	v_and_b32_e32 v19, 0xffff0000, v58
	v_xor_b32_e32 v23, 0x80000000, v21
	v_xor_b32_e32 v22, 0x80000000, v20
	v_pk_fma_f32 v[16:17], v[16:17], 0.5, v[22:23] op_sel_hi:[1,0,1]
	v_xor_b32_e32 v23, 0x80000000, v19
	v_xor_b32_e32 v22, 0x80000000, v18
	v_pk_fma_f32 v[14:15], v[14:15], 0.5, v[22:23] op_sel_hi:[1,0,1]
	v_pk_fma_f32 v[12:13], v[16:17], v[216:217], v[20:21]
	v_pk_fma_f32 v[10:11], v[14:15], v[214:215], v[18:19]
	ds_write_b128 v27, v[10:13] offset:8192
	v_lshlrev_b32_e32 v16, 16, v67
	v_and_b32_e32 v17, 0xffff0000, v67
	v_lshlrev_b32_e32 v20, 16, v69
	v_and_b32_e32 v21, 0xffff0000, v69
	v_lshlrev_b32_e32 v14, 16, v66
	v_and_b32_e32 v15, 0xffff0000, v66
	v_lshlrev_b32_e32 v18, 16, v68
	v_and_b32_e32 v19, 0xffff0000, v68
	v_pk_add_f32 v[16:17], v[20:21], v[16:17]
	v_lshlrev_b32_e32 v20, 16, v65
	v_and_b32_e32 v21, 0xffff0000, v65
	v_pk_add_f32 v[14:15], v[18:19], v[14:15]
	v_lshlrev_b32_e32 v18, 16, v64
	v_and_b32_e32 v19, 0xffff0000, v64
	v_xor_b32_e32 v23, 0x80000000, v21
	v_xor_b32_e32 v22, 0x80000000, v20
	v_pk_fma_f32 v[16:17], v[16:17], 0.5, v[22:23] op_sel_hi:[1,0,1]
	v_xor_b32_e32 v23, 0x80000000, v19
	v_xor_b32_e32 v22, 0x80000000, v18
	v_pk_fma_f32 v[14:15], v[14:15], 0.5, v[22:23] op_sel_hi:[1,0,1]
	v_pk_fma_f32 v[12:13], v[16:17], v[220:221], v[20:21]
	v_pk_fma_f32 v[10:11], v[14:15], v[218:219], v[18:19]
	ds_write_b128 v27, v[10:13] offset:16384
	v_lshlrev_b32_e32 v14, 16, v72
	v_and_b32_e32 v15, 0xffff0000, v72
	v_lshlrev_b32_e32 v18, 16, v74
	v_and_b32_e32 v19, 0xffff0000, v74
	v_pk_add_f32 v[14:15], v[18:19], v[14:15]
	v_lshlrev_b32_e32 v18, 16, v70
	v_and_b32_e32 v19, 0xffff0000, v70
	v_xor_b32_e32 v23, 0x80000000, v19
	v_xor_b32_e32 v22, 0x80000000, v18
	v_pk_fma_f32 v[14:15], v[14:15], 0.5, v[22:23] op_sel_hi:[1,0,1]
	v_lshlrev_b32_e32 v16, 16, v73
	v_pk_fma_f32 v[10:11], v[14:15], v[222:223], v[18:19]
	v_and_b32_e32 v17, 0xffff0000, v73
	v_lshlrev_b32_e32 v20, 16, v75
	v_and_b32_e32 v21, 0xffff0000, v75
	v_add_f32_e32 v10, v10, v10
	v_pk_add_f32 v[16:17], v[20:21], v[16:17]
	v_lshlrev_b32_e32 v20, 16, v71
	v_and_b32_e32 v21, 0xffff0000, v71
	v_mul_f32_e32 v10, 0x3fb8aa3b, v10
	v_xor_b32_e32 v23, 0x80000000, v21
	v_xor_b32_e32 v22, 0x80000000, v20
	v_exp_f32_e32 v14, v10
	v_add_f32_e32 v10, v11, v11
	v_pk_fma_f32 v[16:17], v[16:17], 0.5, v[22:23] op_sel_hi:[1,0,1]
	v_mul_f32_e32 v10, 0x3fb8aa3b, v10
	v_exp_f32_e32 v15, v10
	v_pk_fma_f32 v[10:11], v[16:17], v[224:225], v[20:21]
	v_add_f32_e32 v12, 1.0, v14
	v_add_f32_e32 v10, v10, v10
	v_add_f32_e32 v11, v11, v11
	v_mul_f32_e32 v10, 0x3fb8aa3b, v10
	v_mul_f32_e32 v11, 0x3fb8aa3b, v11
	v_exp_f32_e32 v10, v10
	v_exp_f32_e32 v11, v11
	v_add_f32_e32 v13, 1.0, v15
	v_rcp_f32_e32 v12, v12
	v_add_f32_e32 v10, 1.0, v10
	v_add_f32_e32 v11, 1.0, v11
	v_rcp_f32_e32 v13, v13
	v_rcp_f32_e32 v10, v10
	v_rcp_f32_e32 v11, v11
	v_lshlrev_b32_e32 v24, 3, v8
	v_mul_lo_u32 v26, v9, s76
	v_pk_fma_f32 v[12:13], v[12:13], 2.0, 1.0 op_sel_hi:[1,0,0] neg_lo:[1,0,0] neg_hi:[1,0,0]
	v_pk_fma_f32 v[10:11], v[10:11], 2.0, 1.0 op_sel_hi:[1,0,0] neg_lo:[1,0,0] neg_hi:[1,0,0]
	v_add3_u32 v14, s74, v24, v26
	v_cvt_pk_bf16_f32 v12, v12, v13
	v_cvt_pk_bf16_f32 v13, v10, v11
	ds_write_b64 v14, v[12:13]
	v_lshlrev_b32_e32 v14, 16, v78
	v_and_b32_e32 v15, 0xffff0000, v78
	v_lshlrev_b32_e32 v18, 16, v80
	v_and_b32_e32 v19, 0xffff0000, v80
	v_lshlrev_b32_e32 v16, 16, v79
	v_and_b32_e32 v17, 0xffff0000, v79
	v_lshlrev_b32_e32 v20, 16, v81
	v_and_b32_e32 v21, 0xffff0000, v81
	v_pk_add_f32 v[14:15], v[18:19], v[14:15]
	v_lshlrev_b32_e32 v18, 16, v76
	v_and_b32_e32 v19, 0xffff0000, v76
	v_pk_add_f32 v[16:17], v[20:21], v[16:17]
	v_lshlrev_b32_e32 v20, 16, v77
	v_and_b32_e32 v21, 0xffff0000, v77
	v_xor_b32_e32 v23, 0x80000000, v19
	v_xor_b32_e32 v22, 0x80000000, v18
	v_pk_fma_f32 v[14:15], v[14:15], 0.5, v[22:23] op_sel_hi:[1,0,1]
	v_xor_b32_e32 v23, 0x80000000, v21
	v_xor_b32_e32 v22, 0x80000000, v20
	v_pk_fma_f32 v[16:17], v[16:17], 0.5, v[22:23] op_sel_hi:[1,0,1]
	v_pk_fma_f32 v[10:11], v[14:15], v[226:227], v[18:19]
	v_pk_fma_f32 v[12:13], v[16:17], v[228:229], v[20:21]
	v_cvt_pk_bf16_f32 v10, v10, v11
	v_cvt_pk_bf16_f32 v11, v12, v13
	v_cndmask_b32_e64 v12, 0, 1, s[36:37]
	v_add3_u32 v24, s75, v24, v26
	v_cmp_ne_u32_e64 s[12:13], 1, v12
	s_andn2_b64 vcc, exec, s[36:37]
	ds_write_b64 v24, v[10:11]
	s_cbranch_vccnz .LBB0_491
	v_lshlrev_b32_e32 v12, 16, v51
	v_lshlrev_b32_e32 v13, 16, v49
	v_lshlrev_b32_e32 v10, 16, v47
	v_add_f32_e32 v12, v12, v13
	v_fma_f32 v12, v12, 0.5, -v10
	v_fmac_f32_e32 v10, v12, v230
	v_mul_f32_e32 v10, 0xbfb8aa3b, v10
	v_exp_f32_e32 v12, v10
	v_add_u32_e32 v10, s46, v9
	v_ashrrev_i32_e32 v11, 31, v10
	v_lshl_add_u64 v[10:11], s[40:41], 0, v[10:11]
	v_add_f32_e32 v9, 1.0, v12
	v_rcp_f32_e32 v9, v9
	v_lshlrev_b64 v[10:11], 8, v[10:11]
	v_lshl_add_u64 v[10:11], s[42:43], 0, v[10:11]
	v_lshlrev_b32_e32 v8, 1, v8
	v_cvt_pk_bf16_f32 v12, v9, s0
	v_mov_b32_e32 v9, v38
	v_lshl_add_u64 v[8:9], v[10:11], 0, v[8:9]
	global_store_short v[8:9], v12, off

; #define LAS __attribute__((address_space(3)))
; __device__ __forceinline__ float frcp(float x) { return __builtin_amdgcn_rcpf(x); }
; __device__ __forceinline__ float sigmoidf_(float x) { return frcp(1.0f + __expf(-x)); }
; __device__ __forceinline__ void rwkv_chain(LAS unsigned char* lds, int cid, const bf16_t* P0, const float* mu, const float* w0, const float* w2, const float* a0, const float* a2, ...
;     ...
;         { RW_IDS const int mat = wid >> 2, ntile = wid & 3; const LAS bf16_t* Aop = mat ? wdB : adB; const LAS bf16_t* Bop = mat ? w2B : a2B; LAS float* pre = mat ? preW : preA;
; #pragma unroll
;           for (int mt = 0; mt < 2; ++mt) { f32x4 acc = (f32x4){0.f, 0.f, 0.f, 0.f};
; #pragma unroll
;               for (int ks = 0; ks < 2; ++ks) acc = mfma16(ldsfrag(Bop, 72, ntile * 16, ks * 32, fr, fq), ldsfrag(Aop, 72, mt * 16, ks * 32, fr, fq), acc);
;               *(LAS f32x4*)(pre + (mt * 16 + fr) * 64 + ntile * 16 + fq * 4) = acc; } }
;         __syncthreads();
;         { RW_IDS const int tok = tid >> 4, c0 = (tid & 15) * 4; float kkr[4], av[4], kp[4], wv[4]; float ss = 0.f, bon = 0.f;
; #pragma unroll
;           for (int i = 0; i < 4; ++i) { const int c = c0 + i, ix = tok * 64 + c;
;               const float a = sigmoidf_(cst[c] + preA[ix]); const float sg = sigmoidf_(cst[64 + c] + preW[ix]);
;               wv[i] = -0.60653065971f * sg;
;               const float kraw = kS[ix]; kkr[i] = kraw * cst[128 + c]; ss += kkr[i] * kkr[i];
;               kp[i] = kraw * (1.0f + (a - 1.0f) * cst[192 + c]); av[i] = a; bon += rS[ix] * kp[i] * cst[256 + c]; }
;           ss += dppf<0xB1>(ss); bon += dppf<0xB1>(bon); ss += dppf<0x4E>(ss); bon += dppf<0x4E>(bon);
;           ss += dppf<0x141>(ss); bon += dppf<0x141>(bon); ss += dppf<0x140>(ss); bon += dppf<0x140>(bon);
;           const float inv = frcp(fmaxf(__builtin_amdgcn_sqrtf(ss), 1e-12f));
;           f32x4 o_nk, o_b, o_k, o_w;
; #pragma unroll
;           for (int i = 0; i < 4; ++i) { const float kk = kkr[i] * inv; o_nk[i] = -kk; o_b[i] = kk * av[i]; o_k[i] = kp[i]; o_w[i] = wv[i]; }
;           *(LAS f32x4*)(nkS + tok * 64 + c0) = o_nk; *(LAS f32x4*)(bS + tok * 64 + c0) = o_b; *(LAS f32x4*)(kS + tok * 64 + c0) = o_k; *(LAS f32x4*)(wS + tok * 64 + c0) = o_w;
;           if (dir == 0 && (tid & 15) == 0) BONUS[((size_t)b * SEQ + t0 + tok) * 8 + h] = bon; }
.LBB0_512:
	v_mov_b32_e32 v8, v200
	s_nop 0
	v_readfirstlane_b32 s7, v8
	v_and_b32_e32 v20, 15, v8
	s_bfe_u32 s12, s7, 0x20006
	v_and_b32_e32 v24, 48, v8
	s_cmpk_lt_u32 s7, 0x100
	v_lshl_or_b32 v8, s12, 4, v20
	s_cselect_b32 s13, s58, s59
	v_mul_u32_u24_e32 v8, 0x90, v8
	v_add3_u32 v25, s13, v8, v24
	ds_read_b128 v[8:11], v25
	s_cselect_b32 s7, s75, s74
	v_mul_u32_u24_e32 v12, 0x90, v20
	v_add3_u32 v26, s7, v24, v12
	ds_read_b128 v[12:15], v26
	ds_read_b128 v[16:19], v25 offset:64
	v_lshlrev_b32_e32 v27, 8, v20
	ds_read_b128 v[20:23], v26 offset:64
	s_waitcnt lgkmcnt(2)
	v_mfma_f32_16x16x32_bf16 v[8:11], v[8:11], v[12:15], 0
	s_cselect_b32 s7, s77, s78
	s_lshl_b32 s12, s12, 6
	s_add_i32 s12, s12, s7
	s_waitcnt lgkmcnt(0)
	v_mfma_f32_16x16x32_bf16 v[8:11], v[16:19], v[20:23], v[8:11]
	v_add3_u32 v24, s12, v27, v24
	s_nop 6
	ds_write_b128 v24, v[8:11]
	ds_read_b128 v[8:11], v25
	ds_read_b128 v[12:15], v25 offset:64
	ds_read_b128 v[16:19], v26 offset:2304
	ds_read_b128 v[20:23], v26 offset:2368
	s_waitcnt lgkmcnt(1)
	v_mfma_f32_16x16x32_bf16 v[8:11], v[8:11], v[16:19], 0
	v_mov_b32_e32 v16, v200
	s_waitcnt lgkmcnt(0)
	v_mfma_f32_16x16x32_bf16 v[8:11], v[12:15], v[20:23], v[8:11]
	s_nop 7
	ds_write_b128 v24, v[8:11] offset:4096
	s_waitcnt lgkmcnt(0)
	s_barrier
	s_nop 0
	v_ashrrev_i32_e32 v8, 4, v16
	v_and_b32_e32 v39, 15, v16
	v_lshlrev_b32_e32 v9, 4, v39
	v_lshlrev_b32_e32 v126, 8, v8
	v_add_u32_e32 v127, 0, v9
	v_or_b32_e32 v9, v126, v9
	v_add_u32_e32 v9, 0, v9
	ds_read_b128 v[10:13], v9 offset:49152
	ds_read_b128 v[22:25], v9 offset:57344
	ds_read_b128 v[26:29], v9
	ds_read_b128 v[118:121], v9 offset:8192
	v_mov_b64_e32 v[14:15], v[232:233]
	v_mov_b64_e32 v[16:17], v[234:235]
	v_mov_b64_e32 v[18:19], v[236:237]
	v_mov_b64_e32 v[20:21], v[238:239]
	v_mov_b64_e32 v[30:31], v[248:249]
	v_mov_b64_e32 v[32:33], v[250:251]
	v_mov_b64_e32 v[114:115], v[244:245]
	v_mov_b64_e32 v[116:117], v[246:247]
	v_mov_b64_e32 v[122:123], v[240:241]
	v_mov_b64_e32 v[124:125], v[242:243]
	s_waitcnt lgkmcnt(3)
	v_add_f32_e32 v10, v14, v10
	v_mul_f32_e32 v10, 0xbfb8aa3b, v10
	s_waitcnt lgkmcnt(2)
	v_add_f32_e32 v14, v18, v22
	v_exp_f32_e32 v10, v10
	v_mul_f32_e32 v14, 0xbfb8aa3b, v14
	v_exp_f32_e32 v14, v14
	v_add_f32_e32 v11, v15, v11
	v_mul_f32_e32 v11, 0xbfb8aa3b, v11
	v_exp_f32_e32 v11, v11
	v_add_f32_e32 v10, 1.0, v10
	v_rcp_f32_e32 v22, v10
	v_add_f32_e32 v10, 1.0, v14
	v_add_f32_e32 v14, v19, v23
	v_mul_f32_e32 v14, 0xbfb8aa3b, v14
	v_exp_f32_e32 v14, v14
	v_rcp_f32_e32 v34, v10
	v_add_f32_e32 v10, 1.0, v11
	v_rcp_f32_e32 v23, v10
	v_add_f32_e32 v10, 1.0, v14
	v_rcp_f32_e32 v35, v10
	v_pk_add_f32 v[10:11], v[22:23], -1.0 op_sel_hi:[1,0]
	v_pk_fma_f32 v[10:11], v[114:115], v[10:11], 1.0 op_sel_hi:[1,1,0]
	s_waitcnt lgkmcnt(0)
	v_pk_mul_f32 v[18:19], v[118:119], v[122:123]
	v_pk_mul_f32 v[14:15], v[118:119], v[10:11]
	v_add_f32_e32 v11, v16, v12
	v_mul_f32_e32 v11, 0xbfb8aa3b, v11
	v_exp_f32_e32 v11, v11
	v_mul_f32_e32 v9, v26, v14
	v_fma_f32 v9, v30, v9, 0
	v_mul_f32_e32 v10, v27, v15
	v_add_f32_e32 v12, v20, v24
	v_fmac_f32_e32 v9, v31, v10
	v_add_f32_e32 v10, 1.0, v11
	v_add_f32_e32 v11, v17, v13
	v_mul_f32_e32 v12, 0xbfb8aa3b, v12
	v_mul_f32_e32 v11, 0xbfb8aa3b, v11
	v_exp_f32_e32 v16, v12
	v_exp_f32_e32 v11, v11
	v_add_f32_e32 v13, v21, v25
	v_mul_f32_e32 v13, 0xbfb8aa3b, v13
	v_rcp_f32_e32 v12, v10
	v_add_f32_e32 v10, 1.0, v16
	v_exp_f32_e32 v16, v13
	v_add_f32_e32 v11, 1.0, v11
	v_rcp_f32_e32 v13, v11
	v_rcp_f32_e32 v26, v10
	v_add_f32_e32 v10, 1.0, v16
	v_rcp_f32_e32 v27, v10
	v_pk_add_f32 v[10:11], v[12:13], -1.0 op_sel_hi:[1,0]
	v_pk_mul_f32 v[20:21], v[120:121], v[124:125]
	v_pk_fma_f32 v[10:11], v[116:117], v[10:11], 1.0 op_sel_hi:[1,1,0]
	v_pk_mul_f32 v[24:25], v[20:21], v[20:21]
	v_pk_mul_f32 v[16:17], v[120:121], v[10:11]
	s_nop 0
	v_mul_f32_e32 v10, v28, v16
	v_fmac_f32_e32 v9, v32, v10
	v_pk_mul_f32 v[10:11], v[18:19], v[18:19]
	s_nop 0
	v_add_f32_e32 v10, v10, v11
	v_add_f32_e32 v10, v10, v24
	v_add_f32_e32 v10, v10, v25
	v_mul_f32_e32 v11, v29, v17
	v_fmac_f32_e32 v9, v33, v11
	v_add_f32_dpp v10, v10, v10 quad_perm:[1,0,3,2] row_mask:0xf bank_mask:0xf bound_ctrl:1
	v_add_u32_e32 v11, v127, v126
	v_add_f32_dpp v9, v9, v9 quad_perm:[1,0,3,2] row_mask:0xf bank_mask:0xf bound_ctrl:1
	v_add_f32_dpp v10, v10, v10 quad_perm:[2,3,0,1] row_mask:0xf bank_mask:0xf bound_ctrl:1
	s_nop 0
	v_add_f32_dpp v9, v9, v9 quad_perm:[2,3,0,1] row_mask:0xf bank_mask:0xf bound_ctrl:1
	v_add_f32_dpp v10, v10, v10 row_half_mirror row_mask:0xf bank_mask:0xf bound_ctrl:1
	s_nop 0
	v_add_f32_dpp v9, v9, v9 row_half_mirror row_mask:0xf bank_mask:0xf bound_ctrl:1
	v_add_f32_dpp v10, v10, v10 row_mirror row_mask:0xf bank_mask:0xf bound_ctrl:1
	v_sqrt_f32_e32 v10, v10
	s_nop 0
	v_max_f32_e32 v10, 0x2b8cbccc, v10
	v_rcp_f32_e32 v24, v10
	s_nop 0
	v_mov_b32_dpp v10, v9 row_mirror row_mask:0xf bank_mask:0xf bound_ctrl:1
	v_pk_mul_f32 v[28:29], v[18:19], v[24:25] op_sel_hi:[1,0]
	v_pk_mul_f32 v[24:25], v[20:21], v[24:25] op_sel_hi:[1,0]
	v_xor_b32_e32 v19, 0x80000000, v29
	v_xor_b32_e32 v18, 0x80000000, v28
	v_xor_b32_e32 v20, 0x80000000, v24
	v_xor_b32_e32 v21, 0x80000000, v25
	v_pk_mul_f32 v[22:23], v[22:23], v[28:29]
	v_pk_mul_f32 v[24:25], v[12:13], v[24:25]
	v_pk_mul_f32 v[28:29], v[26:27], s[34:35] op_sel_hi:[1,0]
	v_pk_mul_f32 v[26:27], v[34:35], s[34:35] op_sel_hi:[1,0]
	ds_write_b128 v11, v[18:21] offset:32768
	ds_write_b128 v11, v[22:25] offset:40960
	ds_write_b128 v11, v[14:17] offset:8192
	ds_write_b128 v11, v[26:29] offset:24576
	v_or_b32_e32 v11, s87, v39
	v_cmp_eq_u32_e32 vcc, 0, v11
	s_and_saveexec_b64 s[12:13], vcc
	s_cbranch_execz .LBB0_514
	s_add_u32 s14, s40, s46
	v_add_f32_e32 v10, v9, v10
	v_ashrrev_i32_e32 v9, 31, v8
	s_addc_u32 s15, s41, s47
	v_lshl_add_u64 v[8:9], s[14:15], 0, v[8:9]
	v_lshlrev_b64 v[8:9], 5, v[8:9]
	v_lshl_add_u64 v[8:9], s[44:45], 0, v[8:9]
	global_store_dword v[8:9], v10, off

; #define LAS __attribute__((address_space(3)))
; template <int CTRL> __device__ __forceinline__ float dppf(float x) { return __builtin_bit_cast(float, __builtin_amdgcn_mov_dpp(__builtin_bit_cast(int, x), CTRL, 0xf, 0xf, true)); }
; __device__ __forceinline__ f32x4 mfma16(bf16x8 bfrag, bf16x8 afrag, f32x4 acc) { return __builtin_amdgcn_mfma_f32_16x16x32_bf16(bfrag, afrag, acc, 0, 0, 0); }
; __device__ __forceinline__ void rwkv_chain(LAS unsigned char* lds, int cid, const bf16_t* P0, const float* mu, const float* w0, const float* w2, const float* a0, const float* a2, ...
;     ...
;         f32x4 oacc = (f32x4){0.f, 0.f, 0.f, 0.f};
;         { RW_IDS f32x4 wacc = (f32x4){0.f, 0.f, 0.f, 0.f};
; #pragma unroll
;           for (int ks = 0; ks < 2; ++ks) { const bf16x8 sf = ldsfrag(S0b, 72, vt * 16, ks * 32, fr, fq);
;               wacc = mfma16(ldsfrag(At, 72, tt2 * 16, ks * 32, fr, fq), sf, wacc); oacc = mfma16(ldsfrag(Rt, 72, tt2 * 16, ks * 32, fr, fq), sf, oacc); }
;           const bf16x8 vf = ldsfrag(VT, 40, vt * 16, 0, fr, fq);
;           wacc = mfma16(ldsfrag(NakT, 40, tt2 * 16, 0, fr, fq), vf, wacc); oacc = mfma16(ldsfrag(MkrT, 40, tt2 * 16, 0, fr, fq), vf, oacc);
; #pragma unroll
;           for (int n2 = 0; n2 < 2; ++n2) st[n2] = mfma16(ldsfrag(KtT, 40, (tt2 * 2 + n2) * 16, 0, fr, fq), vf, st[n2]);
; #pragma unroll
;           for (int e = 0; e < 4; ++e) WS[(tt2 * 16 + fq * 4 + e) * 64 + vt * 16 + fr] = wacc[e]; }
;         __syncthreads();
;         { RW_IDS if (wid < 4) { const int v = wid * 16 + (lane >> 2), p = lane & 3; const LAS float* NTp = NT4 + p * 384; float u[8];
; #pragma unroll
;             for (int j = 0; j < 8; ++j) u[j] = 0.f;
; #pragma unroll
;             for (int t = 0; t < 32; ++t) { float q0 = (p == 0) ? WS[t * 64 + v] : 0.f, q1 = 0.f;
; #pragma unroll
;                 for (int j4 = 0; j4 < ((t + 3) / 4 + 3) / 4; ++j4) { const f32x4 nv = *(const LAS f32x4*)(NTp + t * 12 + j4 * 4);
;                     q0 += u[j4 * 4] * nv[0]; q1 += u[j4 * 4 + 1] * nv[1]; q0 += u[j4 * 4 + 2] * nv[2]; q1 += u[j4 * 4 + 3] * nv[3]; }
;                 float q = q0 + q1; q += dppf<0xB1>(q); q += dppf<0x4E>(q);
;                 u[t >> 2] = ((t & 3) == p) ? q : u[t >> 2]; asm volatile("" ::: "memory"); }
.LBB0_534:
	v_mov_b32_e32 v8, v200
	s_waitcnt lgkmcnt(0)
	s_barrier
	s_add_i32 s14, 0, 0x1d800
	v_readfirstlane_b32 s7, v8
	s_bfe_u32 s12, s7, 0x10006
	s_ashr_i32 s7, s7, 3
	v_and_b32_e32 v39, 15, v8
	v_bfe_u32 v118, v8, 4, 2
	v_bfi_b32 v8, -16, s7, v8
	v_mul_lo_u32 v28, v8, s76
	v_mul_lo_u32 v13, v8, s83
	v_lshl_or_b32 v8, s12, 5, v39
	v_lshlrev_b32_e32 v114, 4, v118
	v_lshl_or_b32 v12, s12, 4, v39
	v_mul_u32_u24_e32 v8, 0x50, v8
	v_mul_u32_u24_e32 v9, 0x48, v12
	v_add3_u32 v14, s14, v114, v8
	v_lshlrev_b32_e32 v115, 1, v9
	ds_read_b128 v[8:11], v14
	s_add_i32 s13, 0, 0x1ec00
	v_mul_u32_u24_e32 v17, 40, v12
	v_add3_u32 v16, s13, v13, v114
	s_add_i32 s13, 0, 0x23c00
	v_lshlrev_b32_e32 v24, 1, v17
	v_add3_u32 v20, s13, v24, v114
	ds_read_b128 v[12:15], v14 offset:1280
	ds_read_b128 v[16:19], v16
	ds_read_b128 v[20:23], v20
	s_add_i32 s13, 0, 0x25000
	v_add3_u32 v29, s79, v115, v114
	v_add3_u32 v24, s13, v24, v114
	ds_read_b128 v[24:27], v24
	s_waitcnt lgkmcnt(2)
	v_mfma_f32_16x16x32_bf16 v[0:3], v[8:11], v[16:19], v[0:3]
	ds_read_b128 v[8:11], v29
	v_add3_u32 v32, s85, v28, v114
	ds_read_b128 v[28:31], v29 offset:64
	v_mfma_f32_16x16x32_bf16 v[4:7], v[12:15], v[16:19], v[4:7]
	ds_read_b128 v[12:15], v32
	ds_read_b128 v[32:35], v32 offset:64
	v_add3_u32 v114, s82, v115, v114
	s_and_b32 s7, s7, -16
	s_waitcnt lgkmcnt(1)
	v_mfma_f32_16x16x32_bf16 v[8:11], v[8:11], v[12:15], 0
	s_lshl_b32 s7, s7, 2
	s_add_i32 s7, s7, 0
	s_waitcnt lgkmcnt(0)
	v_mfma_f32_16x16x32_bf16 v[8:11], v[28:31], v[32:35], v[8:11]
	ds_read_b128 v[28:31], v114
	ds_read_b128 v[114:117], v114 offset:64
	v_mfma_f32_16x16x32_bf16 v[8:11], v[20:23], v[16:19], v[8:11]
	s_mul_i32 s7, s7, 36
	v_mul_u32_u24_e32 v20, 0x90, v39
	v_lshl_add_u32 v21, v118, 4, s7
	s_lshl_b32 s7, s12, 6
	s_waitcnt lgkmcnt(1)
	v_mfma_f32_16x16x32_bf16 v[12:15], v[28:31], v[12:15], 0
	v_add3_u32 v20, v20, v21, s7
	s_nop 1
	ds_write_b128 v20, v[8:11] offset:49152
	s_waitcnt lgkmcnt(0)
	v_mfma_f32_16x16x32_bf16 v[8:11], v[114:117], v[32:35], v[12:15]
	s_barrier
	s_nop 1
	v_mov_b32_e32 v12, v200
	v_mfma_f32_16x16x32_bf16 v[8:11], v[24:27], v[16:19], v[8:11]
	s_nop 0
	v_readfirstlane_b32 s7, v12
	s_ashr_i32 s7, s7, 6
	s_cmp_gt_i32 s7, 3
	s_cbranch_scc1 .LBB0_488
	v_bfe_u32 v13, v12, 2, 4
	v_and_b32_e32 v14, 3, v12
	v_lshl_or_b32 v13, s7, 4, v13
	v_cmp_eq_u32_e32 vcc, 0, v14
	v_cmp_eq_u32_e64 s[14:15], 1, v14
	v_cmp_eq_u32_e64 s[12:13], 2, v14
	v_cmp_eq_u32_e64 s[16:17], 3, v14
	v_mul_u32_u24_e32 v12, 0x90, v13
	s_movk_i32 s7, 0x410
	v_mov_b32_e32 v15, s84
	v_mul_lo_u32 v28, v13, s83
	v_mad_u32_u24 v15, v14, s7, v15
	v_lshl_add_u32 v28, v14, 1, v28
	ds_read_b128 v[162:165], v12 offset:49152
	ds_read_b128 v[166:169], v12 offset:49168
	ds_read_b128 v[170:173], v12 offset:49184
	ds_read_b128 v[174:177], v12 offset:49200
	ds_read_b128 v[178:181], v12 offset:49216
	ds_read_b128 v[182:185], v12 offset:49232
	ds_read_b128 v[186:189], v12 offset:49248
	ds_read_b128 v[190:193], v12 offset:49264
	ds_read_b32 v122, v15 offset:32
	ds_read_b32 v130, v15 offset:64
	ds_read_b32 v138, v15 offset:96
	ds_read_b32 v146, v15 offset:128
	ds_read_b64 v[154:155], v15 offset:160
	s_waitcnt lgkmcnt(12)
	v_cndmask_b32_e32 v16, 0, v162, vcc
	ds_read_b64 v[114:115], v15 offset:192
	s_waitcnt lgkmcnt(5)
	v_cndmask_b32_e32 v26, 0, v163, vcc
	v_fmac_f32_e32 v26, v16, v122
	ds_read_b64 v[122:123], v15 offset:224
	s_nop 0
	v_add_f32_dpp v26, v26, v26 quad_perm:[1,0,3,2] row_mask:0xf bank_mask:0xf bound_ctrl:1
	s_waitcnt lgkmcnt(5)
	s_nop 0
	v_add_f32_dpp v26, v26, v26 quad_perm:[2,3,0,1] row_mask:0xf bank_mask:0xf bound_ctrl:1
	v_cndmask_b32_e32 v24, 0, v164, vcc
	v_cndmask_b32_e64 v16, v16, v26, s[14:15]
	v_fmac_f32_e32 v24, v16, v130
	ds_read_b64 v[130:131], v15 offset:256
	s_nop 0
	v_add_f32_dpp v24, v24, v24 quad_perm:[1,0,3,2] row_mask:0xf bank_mask:0xf bound_ctrl:1
	s_waitcnt lgkmcnt(5)
	s_nop 0
	v_add_f32_dpp v24, v24, v24 quad_perm:[2,3,0,1] row_mask:0xf bank_mask:0xf bound_ctrl:1
	v_cndmask_b32_e32 v26, 0, v165, vcc
	v_cndmask_b32_e64 v16, v16, v24, s[12:13]
	v_fmac_f32_e32 v26, v16, v138
	ds_read_b128 v[138:141], v15 offset:288
	s_nop 0
	v_add_f32_dpp v26, v26, v26 quad_perm:[1,0,3,2] row_mask:0xf bank_mask:0xf bound_ctrl:1
	s_waitcnt lgkmcnt(5)
	s_nop 0
	v_add_f32_dpp v26, v26, v26 quad_perm:[2,3,0,1] row_mask:0xf bank_mask:0xf bound_ctrl:1
	v_cndmask_b32_e32 v24, 0, v166, vcc
	v_cndmask_b32_e64 v16, v16, v26, s[16:17]
	v_fmac_f32_e32 v24, v16, v146
	ds_read_b128 v[146:149], v15 offset:320
	s_waitcnt lgkmcnt(5)
	v_add_f32_dpp v24, v24, v24 quad_perm:[1,0,3,2] row_mask:0xf bank_mask:0xf bound_ctrl:1
	v_cndmask_b32_e32 v26, 0, v167, vcc
	s_nop 0
	v_add_f32_dpp v24, v24, v24 quad_perm:[2,3,0,1] row_mask:0xf bank_mask:0xf bound_ctrl:1
	v_fmac_f32_e32 v26, v16, v154
	v_cndmask_b32_e32 v17, 0, v24, vcc
	v_fmac_f32_e32 v26, v17, v155
	ds_read_b128 v[154:157], v15 offset:352
	s_waitcnt lgkmcnt(5)
	v_add_f32_dpp v26, v26, v26 quad_perm:[1,0,3,2] row_mask:0xf bank_mask:0xf bound_ctrl:1
	v_cndmask_b32_e32 v24, 0, v168, vcc
	s_nop 0
	v_add_f32_dpp v26, v26, v26 quad_perm:[2,3,0,1] row_mask:0xf bank_mask:0xf bound_ctrl:1
	v_fmac_f32_e32 v24, v16, v114
	v_cndmask_b32_e64 v17, v17, v26, s[14:15]
	v_fmac_f32_e32 v24, v17, v115
	ds_read_b128 v[114:117], v15 offset:384
	s_waitcnt lgkmcnt(5)
	v_add_f32_dpp v24, v24, v24 quad_perm:[1,0,3,2] row_mask:0xf bank_mask:0xf bound_ctrl:1
	v_cndmask_b32_e32 v26, 0, v169, vcc
	s_nop 0
	v_add_f32_dpp v24, v24, v24 quad_perm:[2,3,0,1] row_mask:0xf bank_mask:0xf bound_ctrl:1
	v_fmac_f32_e32 v26, v16, v122
	v_cndmask_b32_e64 v17, v17, v24, s[12:13]
	v_fmac_f32_e32 v26, v17, v123
	ds_read_b128 v[122:125], v15 offset:416
	s_waitcnt lgkmcnt(5)
; #define LAS __attribute__((address_space(3)))
; template <int CTRL> __device__ __forceinline__ float dppf(float x) { return __builtin_bit_cast(float, __builtin_amdgcn_mov_dpp(__builtin_bit_cast(int, x), CTRL, 0xf, 0xf, true)); }
; __device__ __forceinline__ void rwkv_chain(LAS unsigned char* lds, int cid, const bf16_t* P0, const float* mu, const float* w0, const float* w2, const float* a0, const float* a2, ...
;     ...
;         { RW_IDS if (wid < 4) { const int v = wid * 16 + (lane >> 2), p = lane & 3; const LAS float* NTp = NT4 + p * 384; float u[8];
; #pragma unroll
;             for (int j = 0; j < 8; ++j) u[j] = 0.f;
; #pragma unroll
;             for (int t = 0; t < 32; ++t) { float q0 = (p == 0) ? WS[t * 64 + v] : 0.f, q1 = 0.f;
; #pragma unroll
;                 for (int j4 = 0; j4 < ((t + 3) / 4 + 3) / 4; ++j4) { const f32x4 nv = *(const LAS f32x4*)(NTp + t * 12 + j4 * 4);
;                     q0 += u[j4 * 4] * nv[0]; q1 += u[j4 * 4 + 1] * nv[1]; q0 += u[j4 * 4 + 2] * nv[2]; q1 += u[j4 * 4 + 3] * nv[3]; }
;                 float q = q0 + q1; q += dppf<0xB1>(q); q += dppf<0x4E>(q);
;                 u[t >> 2] = ((t & 3) == p) ? q : u[t >> 2]; asm volatile("" ::: "memory"); }
	v_add_f32_dpp v26, v26, v26 quad_perm:[1,0,3,2] row_mask:0xf bank_mask:0xf bound_ctrl:1
	v_cndmask_b32_e32 v24, 0, v170, vcc
	s_nop 0
	v_add_f32_dpp v26, v26, v26 quad_perm:[2,3,0,1] row_mask:0xf bank_mask:0xf bound_ctrl:1
	v_fmac_f32_e32 v24, v16, v130
	v_cndmask_b32_e64 v17, v17, v26, s[16:17]
	v_fmac_f32_e32 v24, v17, v131
	ds_read_b128 v[130:133], v15 offset:448
	s_waitcnt lgkmcnt(5)
	v_add_f32_dpp v24, v24, v24 quad_perm:[1,0,3,2] row_mask:0xf bank_mask:0xf bound_ctrl:1
	v_cndmask_b32_e32 v26, 0, v171, vcc
	v_fmac_f32_e32 v26, v16, v138
	v_add_f32_dpp v24, v24, v24 quad_perm:[2,3,0,1] row_mask:0xf bank_mask:0xf bound_ctrl:1
	v_mul_f32_e32 v27, v17, v139
	v_add_f32_e32 v26, v26, v27
	v_cndmask_b32_e32 v18, 0, v24, vcc
	v_fmac_f32_e32 v26, v18, v140
	ds_read_b128 v[138:141], v15 offset:480
	s_waitcnt lgkmcnt(5)
	v_add_f32_dpp v26, v26, v26 quad_perm:[1,0,3,2] row_mask:0xf bank_mask:0xf bound_ctrl:1
	v_cndmask_b32_e32 v24, 0, v172, vcc
	v_fmac_f32_e32 v24, v16, v146
	v_add_f32_dpp v26, v26, v26 quad_perm:[2,3,0,1] row_mask:0xf bank_mask:0xf bound_ctrl:1
	v_mul_f32_e32 v25, v17, v147
	v_add_f32_e32 v24, v24, v25
	v_cndmask_b32_e64 v18, v18, v26, s[14:15]
	v_fmac_f32_e32 v24, v18, v148
	ds_read_b128 v[146:149], v15 offset:512
	s_waitcnt lgkmcnt(5)
	v_add_f32_dpp v24, v24, v24 quad_perm:[1,0,3,2] row_mask:0xf bank_mask:0xf bound_ctrl:1
	v_cndmask_b32_e32 v26, 0, v173, vcc
	v_fmac_f32_e32 v26, v16, v154
	v_add_f32_dpp v24, v24, v24 quad_perm:[2,3,0,1] row_mask:0xf bank_mask:0xf bound_ctrl:1
	v_mul_f32_e32 v27, v17, v155
	v_add_f32_e32 v26, v26, v27
	v_cndmask_b32_e64 v18, v18, v24, s[12:13]
	v_fmac_f32_e32 v26, v18, v156
	ds_read_b128 v[154:157], v15 offset:544
	ds_read_b32 v158, v15 offset:560
	s_waitcnt lgkmcnt(6)
	v_add_f32_dpp v26, v26, v26 quad_perm:[1,0,3,2] row_mask:0xf bank_mask:0xf bound_ctrl:1
	v_cndmask_b32_e32 v24, 0, v174, vcc
	v_fmac_f32_e32 v24, v16, v114
	v_add_f32_dpp v26, v26, v26 quad_perm:[2,3,0,1] row_mask:0xf bank_mask:0xf bound_ctrl:1
	v_mul_f32_e32 v25, v17, v115
	v_add_f32_e32 v24, v24, v25
	v_cndmask_b32_e64 v18, v18, v26, s[16:17]
	v_fmac_f32_e32 v24, v18, v116
	ds_read_b128 v[114:117], v15 offset:576
	ds_read_b32 v118, v15 offset:592
	s_waitcnt lgkmcnt(7)
	v_add_f32_dpp v24, v24, v24 quad_perm:[1,0,3,2] row_mask:0xf bank_mask:0xf bound_ctrl:1
	v_cndmask_b32_e32 v26, 0, v175, vcc
	v_fmac_f32_e32 v26, v16, v122
	v_mul_f32_e32 v27, v17, v123
	v_add_f32_dpp v24, v24, v24 quad_perm:[2,3,0,1] row_mask:0xf bank_mask:0xf bound_ctrl:1
	v_fmac_f32_e32 v26, v18, v124
	v_add_f32_e32 v26, v26, v27
	v_cndmask_b32_e32 v19, 0, v24, vcc
	v_fmac_f32_e32 v26, v19, v125
	ds_read_b128 v[122:125], v15 offset:608
	ds_read_b32 v126, v15 offset:624
	s_waitcnt lgkmcnt(8)
	v_add_f32_dpp v26, v26, v26 quad_perm:[1,0,3,2] row_mask:0xf bank_mask:0xf bound_ctrl:1
	v_cndmask_b32_e32 v24, 0, v176, vcc
	v_fmac_f32_e32 v24, v16, v130
	v_mul_f32_e32 v25, v17, v131
	v_add_f32_dpp v26, v26, v26 quad_perm:[2,3,0,1] row_mask:0xf bank_mask:0xf bound_ctrl:1
	v_fmac_f32_e32 v24, v18, v132
	v_add_f32_e32 v24, v24, v25
	v_cndmask_b32_e64 v19, v19, v26, s[14:15]
	v_fmac_f32_e32 v24, v19, v133
	ds_read_b128 v[130:133], v15 offset:640
	ds_read_b32 v134, v15 offset:656
	s_waitcnt lgkmcnt(9)
	v_add_f32_dpp v24, v24, v24 quad_perm:[1,0,3,2] row_mask:0xf bank_mask:0xf bound_ctrl:1
	v_cndmask_b32_e32 v26, 0, v177, vcc
	v_fmac_f32_e32 v26, v16, v138
	v_mul_f32_e32 v27, v17, v139
	v_add_f32_dpp v24, v24, v24 quad_perm:[2,3,0,1] row_mask:0xf bank_mask:0xf bound_ctrl:1
	v_fmac_f32_e32 v26, v18, v140
	v_add_f32_e32 v26, v26, v27
	v_cndmask_b32_e64 v19, v19, v24, s[12:13]
	v_fmac_f32_e32 v26, v19, v141
	ds_read_b128 v[138:141], v15 offset:672
	ds_read_b64 v[142:143], v15 offset:688
	s_waitcnt lgkmcnt(10)
	v_add_f32_dpp v26, v26, v26 quad_perm:[1,0,3,2] row_mask:0xf bank_mask:0xf bound_ctrl:1
	v_cndmask_b32_e32 v24, 0, v178, vcc
	v_fmac_f32_e32 v24, v16, v146
	v_mul_f32_e32 v25, v17, v147
	v_add_f32_dpp v26, v26, v26 quad_perm:[2,3,0,1] row_mask:0xf bank_mask:0xf bound_ctrl:1
	v_fmac_f32_e32 v24, v18, v148
	v_add_f32_e32 v24, v24, v25
	v_cndmask_b32_e64 v19, v19, v26, s[16:17]
	v_fmac_f32_e32 v24, v19, v149
	ds_read_b128 v[146:149], v15 offset:704
	ds_read_b64 v[150:151], v15 offset:720
	s_waitcnt lgkmcnt(10)
	v_add_f32_dpp v24, v24, v24 quad_perm:[1,0,3,2] row_mask:0xf bank_mask:0xf bound_ctrl:1
	v_cndmask_b32_e32 v26, 0, v179, vcc
	v_fmac_f32_e32 v26, v16, v154
	v_mul_f32_e32 v27, v17, v155
	v_add_f32_dpp v24, v24, v24 quad_perm:[2,3,0,1] row_mask:0xf bank_mask:0xf bound_ctrl:1
	v_pk_fma_f32 v[26:27], v[18:19], v[156:157], v[26:27]
	v_add_f32_e32 v26, v26, v27
	v_cndmask_b32_e32 v20, 0, v24, vcc
	v_fmac_f32_e32 v26, v20, v158
	ds_read_b128 v[154:157], v15 offset:736
	ds_read_b64 v[158:159], v15 offset:752
	s_waitcnt lgkmcnt(10)
	v_add_f32_dpp v26, v26, v26 quad_perm:[1,0,3,2] row_mask:0xf bank_mask:0xf bound_ctrl:1
	v_cndmask_b32_e32 v24, 0, v180, vcc
	v_fmac_f32_e32 v24, v16, v114
	v_mul_f32_e32 v25, v17, v115
	v_add_f32_dpp v26, v26, v26 quad_perm:[2,3,0,1] row_mask:0xf bank_mask:0xf bound_ctrl:1
	v_pk_fma_f32 v[24:25], v[18:19], v[116:117], v[24:25]
	v_add_f32_e32 v24, v24, v25
	v_cndmask_b32_e64 v20, v20, v26, s[14:15]
	v_fmac_f32_e32 v24, v20, v118
	ds_read_b128 v[114:117], v15 offset:768
	ds_read_b64 v[118:119], v15 offset:784
	s_waitcnt lgkmcnt(10)
	v_add_f32_dpp v24, v24, v24 quad_perm:[1,0,3,2] row_mask:0xf bank_mask:0xf bound_ctrl:1
	v_cndmask_b32_e32 v26, 0, v181, vcc
	v_fmac_f32_e32 v26, v16, v122
	v_mul_f32_e32 v27, v17, v123
	v_add_f32_dpp v24, v24, v24 quad_perm:[2,3,0,1] row_mask:0xf bank_mask:0xf bound_ctrl:1
	v_pk_fma_f32 v[26:27], v[18:19], v[124:125], v[26:27]
	v_add_f32_e32 v26, v26, v27
	v_cndmask_b32_e64 v20, v20, v24, s[12:13]
	v_fmac_f32_e32 v26, v20, v126
	ds_read_b128 v[122:125], v15 offset:800
	ds_read_b128 v[126:129], v15 offset:816
	s_waitcnt lgkmcnt(10)
; #define LAS __attribute__((address_space(3)))
; template <int CTRL> __device__ __forceinline__ float dppf(float x) { return __builtin_bit_cast(float, __builtin_amdgcn_mov_dpp(__builtin_bit_cast(int, x), CTRL, 0xf, 0xf, true)); }
; __device__ __forceinline__ void rwkv_chain(LAS unsigned char* lds, int cid, const bf16_t* P0, const float* mu, const float* w0, const float* w2, const float* a0, const float* a2, ...
;     ...
;         { RW_IDS if (wid < 4) { const int v = wid * 16 + (lane >> 2), p = lane & 3; const LAS float* NTp = NT4 + p * 384; float u[8];
; #pragma unroll
;             for (int j = 0; j < 8; ++j) u[j] = 0.f;
; #pragma unroll
;             for (int t = 0; t < 32; ++t) { float q0 = (p == 0) ? WS[t * 64 + v] : 0.f, q1 = 0.f;
; #pragma unroll
;                 for (int j4 = 0; j4 < ((t + 3) / 4 + 3) / 4; ++j4) { const f32x4 nv = *(const LAS f32x4*)(NTp + t * 12 + j4 * 4);
;                     q0 += u[j4 * 4] * nv[0]; q1 += u[j4 * 4 + 1] * nv[1]; q0 += u[j4 * 4 + 2] * nv[2]; q1 += u[j4 * 4 + 3] * nv[3]; }
;                 float q = q0 + q1; q += dppf<0xB1>(q); q += dppf<0x4E>(q);
;                 u[t >> 2] = ((t & 3) == p) ? q : u[t >> 2]; asm volatile("" ::: "memory"); }
	v_add_f32_dpp v26, v26, v26 quad_perm:[1,0,3,2] row_mask:0xf bank_mask:0xf bound_ctrl:1
	v_cndmask_b32_e32 v24, 0, v182, vcc
	v_fmac_f32_e32 v24, v16, v130
	v_mul_f32_e32 v25, v17, v131
	v_add_f32_dpp v26, v26, v26 quad_perm:[2,3,0,1] row_mask:0xf bank_mask:0xf bound_ctrl:1
	v_pk_fma_f32 v[24:25], v[18:19], v[132:133], v[24:25]
	v_add_f32_e32 v24, v24, v25
	v_cndmask_b32_e64 v20, v20, v26, s[16:17]
	v_fmac_f32_e32 v24, v20, v134
	ds_read_b128 v[130:133], v15 offset:832
	ds_read_b128 v[134:137], v15 offset:848
	s_waitcnt lgkmcnt(10)
	v_add_f32_dpp v24, v24, v24 quad_perm:[1,0,3,2] row_mask:0xf bank_mask:0xf bound_ctrl:1
	v_cndmask_b32_e32 v26, 0, v183, vcc
	v_fmac_f32_e32 v26, v16, v138
	v_mul_f32_e32 v27, v17, v139
	v_add_f32_dpp v24, v24, v24 quad_perm:[2,3,0,1] row_mask:0xf bank_mask:0xf bound_ctrl:1
	v_pk_fma_f32 v[26:27], v[18:19], v[140:141], v[26:27]
	v_fmac_f32_e32 v26, v20, v142
	v_add_f32_e32 v26, v26, v27
	v_cndmask_b32_e32 v21, 0, v24, vcc
	v_fmac_f32_e32 v26, v21, v143
	ds_read_b128 v[138:141], v15 offset:864
	ds_read_b128 v[142:145], v15 offset:880
	s_waitcnt lgkmcnt(10)
	v_add_f32_dpp v26, v26, v26 quad_perm:[1,0,3,2] row_mask:0xf bank_mask:0xf bound_ctrl:1
	v_cndmask_b32_e32 v24, 0, v184, vcc
	v_fmac_f32_e32 v24, v16, v146
	v_mul_f32_e32 v25, v17, v147
	v_add_f32_dpp v26, v26, v26 quad_perm:[2,3,0,1] row_mask:0xf bank_mask:0xf bound_ctrl:1
	v_pk_fma_f32 v[24:25], v[18:19], v[148:149], v[24:25]
	v_fmac_f32_e32 v24, v20, v150
	v_add_f32_e32 v24, v24, v25
	v_cndmask_b32_e64 v21, v21, v26, s[14:15]
	v_fmac_f32_e32 v24, v21, v151
	ds_read_b128 v[146:149], v15 offset:896
	ds_read_b128 v[150:153], v15 offset:912
	s_waitcnt lgkmcnt(10)
	v_add_f32_dpp v24, v24, v24 quad_perm:[1,0,3,2] row_mask:0xf bank_mask:0xf bound_ctrl:1
	v_cndmask_b32_e32 v26, 0, v185, vcc
	v_fmac_f32_e32 v26, v16, v154
	v_mul_f32_e32 v27, v17, v155
	v_add_f32_dpp v24, v24, v24 quad_perm:[2,3,0,1] row_mask:0xf bank_mask:0xf bound_ctrl:1
	v_pk_fma_f32 v[26:27], v[18:19], v[156:157], v[26:27]
	v_fmac_f32_e32 v26, v20, v158
	v_add_f32_e32 v26, v26, v27
	v_cndmask_b32_e64 v21, v21, v24, s[12:13]
	v_fmac_f32_e32 v26, v21, v159
	ds_read_b128 v[154:157], v15 offset:928
	ds_read_b128 v[158:161], v15 offset:944
	s_waitcnt lgkmcnt(10)
	v_add_f32_dpp v26, v26, v26 quad_perm:[1,0,3,2] row_mask:0xf bank_mask:0xf bound_ctrl:1
	v_cndmask_b32_e32 v24, 0, v186, vcc
	v_fmac_f32_e32 v24, v16, v114
	v_mul_f32_e32 v25, v17, v115
	v_add_f32_dpp v26, v26, v26 quad_perm:[2,3,0,1] row_mask:0xf bank_mask:0xf bound_ctrl:1
	v_pk_fma_f32 v[24:25], v[18:19], v[116:117], v[24:25]
	v_fmac_f32_e32 v24, v20, v118
	v_add_f32_e32 v24, v24, v25
	v_cndmask_b32_e64 v21, v21, v26, s[16:17]
	v_fmac_f32_e32 v24, v21, v119
	ds_read_b128 v[114:117], v15 offset:960
	ds_read_b128 v[118:121], v15 offset:976
	s_waitcnt lgkmcnt(10)
	v_add_f32_dpp v24, v24, v24 quad_perm:[1,0,3,2] row_mask:0xf bank_mask:0xf bound_ctrl:1
	v_cndmask_b32_e32 v26, 0, v187, vcc
	v_fmac_f32_e32 v26, v16, v122
	v_mul_f32_e32 v27, v17, v123
	v_add_f32_dpp v24, v24, v24 quad_perm:[2,3,0,1] row_mask:0xf bank_mask:0xf bound_ctrl:1
	v_pk_fma_f32 v[26:27], v[18:19], v[124:125], v[26:27]
	v_pk_fma_f32 v[26:27], v[20:21], v[126:127], v[26:27]
	v_add_f32_e32 v26, v26, v27
	v_cndmask_b32_e32 v22, 0, v24, vcc
	v_fmac_f32_e32 v26, v22, v128
	ds_read_b128 v[122:125], v15 offset:992
	ds_read_b128 v[126:129], v15 offset:1008
	s_waitcnt lgkmcnt(10)
	v_add_f32_dpp v26, v26, v26 quad_perm:[1,0,3,2] row_mask:0xf bank_mask:0xf bound_ctrl:1
	v_cndmask_b32_e32 v24, 0, v188, vcc
	v_fmac_f32_e32 v24, v16, v130
	v_mul_f32_e32 v25, v17, v131
	v_add_f32_dpp v26, v26, v26 quad_perm:[2,3,0,1] row_mask:0xf bank_mask:0xf bound_ctrl:1
	v_pk_fma_f32 v[24:25], v[18:19], v[132:133], v[24:25]
	v_pk_fma_f32 v[24:25], v[20:21], v[134:135], v[24:25]
	v_add_f32_e32 v24, v24, v25
	v_cndmask_b32_e64 v22, v22, v26, s[14:15]
	v_fmac_f32_e32 v24, v22, v136
	s_waitcnt lgkmcnt(8)
; #define LAS __attribute__((address_space(3)))
; __device__ __forceinline__ unsigned f2bf(float f) { return pk2(f, 0.f) & 0xffffu; }
; template <int CTRL> __device__ __forceinline__ float dppf(float x) { return __builtin_bit_cast(float, __builtin_amdgcn_mov_dpp(__builtin_bit_cast(int, x), CTRL, 0xf, 0xf, true)); }
; __device__ __forceinline__ void rwkv_chain(LAS unsigned char* lds, int cid, const bf16_t* P0, const float* mu, const float* w0, const float* w2, const float* a0, const float* a2, ...
;     ...
;             for (int t = 0; t < 32; ++t) { float q0 = (p == 0) ? WS[t * 64 + v] : 0.f, q1 = 0.f;
; #pragma unroll
;                 for (int j4 = 0; j4 < ((t + 3) / 4 + 3) / 4; ++j4) { const f32x4 nv = *(const LAS f32x4*)(NTp + t * 12 + j4 * 4);
;                     q0 += u[j4 * 4] * nv[0]; q1 += u[j4 * 4 + 1] * nv[1]; q0 += u[j4 * 4 + 2] * nv[2]; q1 += u[j4 * 4 + 3] * nv[3]; }
;                 float q = q0 + q1; q += dppf<0xB1>(q); q += dppf<0x4E>(q);
;                 u[t >> 2] = ((t & 3) == p) ? q : u[t >> 2]; asm volatile("" ::: "memory"); }
; #pragma unroll
;             for (int j = 0; j < 8; ++j) Ub[v * 40 + 4 * j + p] = (bf16_t)f2bf(u[j]); } }
	v_cndmask_b32_e32 v26, 0, v189, vcc
	v_fmac_f32_e32 v26, v16, v138
	v_add_f32_dpp v24, v24, v24 quad_perm:[1,0,3,2] row_mask:0xf bank_mask:0xf bound_ctrl:1
	v_mul_f32_e32 v27, v17, v139
	v_pk_fma_f32 v[26:27], v[18:19], v[140:141], v[26:27]
	v_add_f32_dpp v24, v24, v24 quad_perm:[2,3,0,1] row_mask:0xf bank_mask:0xf bound_ctrl:1
	v_pk_fma_f32 v[26:27], v[20:21], v[142:143], v[26:27]
	v_add_f32_e32 v26, v26, v27
	v_cndmask_b32_e64 v22, v22, v24, s[12:13]
	v_fmac_f32_e32 v26, v22, v144
	s_waitcnt lgkmcnt(6)
	v_cndmask_b32_e32 v24, 0, v190, vcc
	v_fmac_f32_e32 v24, v16, v146
	v_add_f32_dpp v26, v26, v26 quad_perm:[1,0,3,2] row_mask:0xf bank_mask:0xf bound_ctrl:1
	v_mul_f32_e32 v25, v17, v147
	v_pk_fma_f32 v[24:25], v[18:19], v[148:149], v[24:25]
	v_add_f32_dpp v26, v26, v26 quad_perm:[2,3,0,1] row_mask:0xf bank_mask:0xf bound_ctrl:1
	v_pk_fma_f32 v[24:25], v[20:21], v[150:151], v[24:25]
	v_add_f32_e32 v24, v24, v25
	v_cndmask_b32_e64 v22, v22, v26, s[16:17]
	v_fmac_f32_e32 v24, v22, v152
	s_waitcnt lgkmcnt(4)
	v_cndmask_b32_e32 v26, 0, v191, vcc
	v_fmac_f32_e32 v26, v16, v154
	v_add_f32_dpp v24, v24, v24 quad_perm:[1,0,3,2] row_mask:0xf bank_mask:0xf bound_ctrl:1
	v_mul_f32_e32 v27, v17, v155
	v_pk_fma_f32 v[26:27], v[18:19], v[156:157], v[26:27]
	v_pk_fma_f32 v[26:27], v[20:21], v[158:159], v[26:27]
	v_add_f32_dpp v24, v24, v24 quad_perm:[2,3,0,1] row_mask:0xf bank_mask:0xf bound_ctrl:1
	v_fmac_f32_e32 v26, v22, v160
	v_add_f32_e32 v26, v26, v27
	v_cndmask_b32_e32 v23, 0, v24, vcc
	v_fmac_f32_e32 v26, v23, v161
	s_waitcnt lgkmcnt(2)
	v_cndmask_b32_e32 v24, 0, v192, vcc
	v_fmac_f32_e32 v24, v16, v114
	v_add_f32_dpp v26, v26, v26 quad_perm:[1,0,3,2] row_mask:0xf bank_mask:0xf bound_ctrl:1
	v_mul_f32_e32 v25, v17, v115
	v_pk_fma_f32 v[24:25], v[18:19], v[116:117], v[24:25]
	v_pk_fma_f32 v[24:25], v[20:21], v[118:119], v[24:25]
	v_add_f32_dpp v26, v26, v26 quad_perm:[2,3,0,1] row_mask:0xf bank_mask:0xf bound_ctrl:1
	v_fmac_f32_e32 v24, v22, v120
	v_add_f32_e32 v24, v24, v25
	v_cndmask_b32_e64 v23, v23, v26, s[14:15]
	v_fmac_f32_e32 v24, v23, v121
	s_waitcnt lgkmcnt(0)
	v_cndmask_b32_e32 v26, 0, v193, vcc
	v_fmac_f32_e32 v26, v16, v122
	v_add_f32_dpp v24, v24, v24 quad_perm:[1,0,3,2] row_mask:0xf bank_mask:0xf bound_ctrl:1
	v_mul_f32_e32 v27, v17, v123
	v_pk_fma_f32 v[26:27], v[18:19], v[124:125], v[26:27]
	v_pk_fma_f32 v[26:27], v[20:21], v[126:127], v[26:27]
	v_add_f32_dpp v24, v24, v24 quad_perm:[2,3,0,1] row_mask:0xf bank_mask:0xf bound_ctrl:1
	v_fmac_f32_e32 v26, v22, v128
	v_add_f32_e32 v26, v26, v27
	v_cndmask_b32_e64 v23, v23, v24, s[12:13]
	v_fmac_f32_e32 v26, v23, v129
	s_nop 1
	v_add_f32_dpp v26, v26, v26 quad_perm:[1,0,3,2] row_mask:0xf bank_mask:0xf bound_ctrl:1
	s_nop 1
	v_add_f32_dpp v26, v26, v26 quad_perm:[2,3,0,1] row_mask:0xf bank_mask:0xf bound_ctrl:1
	v_cndmask_b32_e64 v23, v23, v26, s[16:17]
	v_cvt_pk_bf16_f32 v30, v16, v16
	ds_write_b16 v28, v30 offset:58368
	v_cvt_pk_bf16_f32 v31, v17, v17
	ds_write_b16 v28, v31 offset:58376
	v_cvt_pk_bf16_f32 v30, v18, v18
	ds_write_b16 v28, v30 offset:58384
	v_cvt_pk_bf16_f32 v31, v19, v19
	ds_write_b16 v28, v31 offset:58392
	v_cvt_pk_bf16_f32 v30, v20, v20
	ds_write_b16 v28, v30 offset:58400
	v_cvt_pk_bf16_f32 v31, v21, v21
	ds_write_b16 v28, v31 offset:58408
	v_cvt_pk_bf16_f32 v30, v22, v22
	ds_write_b16 v28, v30 offset:58416
	v_cvt_pk_bf16_f32 v31, v23, v23
	ds_write_b16 v28, v31 offset:58424
	s_branch .LBB0_488
